# on top of v4: attention per-unit relative-bias table: bucket lookup + rel_bias load hoisted one unit ahead so the unit head no longer has a dependent LDS->global round trip between its barriers
# baseline (speedup 1.0000x reference)
; #define LAS __attribute__((address_space(3)))
; __device__ __forceinline__ void attn_mfma(const GAS bf16* proj, GAS bf16* part, GAS float* lse, int TOKG, const GAS float* qgain, const GAS float* kgain, const GAS float* rel_bias,
;                                           unsigned char* lds, int tid, int lane, int wave, int bid, int G) {
;     ...
;     const int c = lane & 31, hh = lane >> 5, c8 = tid & 7, rp2 = tid >> 3;
;     const int vtl = (4 * (lane >> 5) + ((lane & 15) >> 2)) * ATT_VSTR + (16 * ((lane >> 4) & 1) + 4 * (lane & 3)) * 2;
;     float kg[8];
; #pragma unroll
;     for (int e = 0; e < 8; ++e) kg[e] = kgain[c8 * 8 + e];
;     ...
;     v4u kwr[6], vwr[6], qwr[4];
;     ...
;     LAS int* bkt = (LAS int*)(L + ATT_BIAS + 768);
;     for (int e = tid; e < 3 * 129; e += 512) { const int pp = e / 129, dl = e - 129 * pp, dist = dl << (2 * pp); int bk;
;         if (dist < 16) bk = dist; else { const float scl = logf((float)dist / 16.f) / logf(128.f); const int lg = 16 + (int)(scl * 16.f); bk = lg < 31 ? lg : 31; }
;         bkt[e] = bk; }
;     __syncthreads();
;     if (bid < nunits) ATT_ISSUE(bid);
;     for (int u = bid; u < nunits; u += G) {
;         ATT_DEC(u, )
;         __syncthreads();
;         if (tid < 192) { float tv = -INFINITY; const int dl = 160 - tid;
;             if (dl >= 0 && dl <= 128) tv = rel_bias[bkt[p * 129 + dl] * 16 + h] * 1.4426950408889634f;
;             ((LAS float*)(L + ATT_BIAS))[tid] = tv; }
; #pragma unroll
;         for (int j = 0; j < 3; ++j) {
;             const int kk0 = 2 * rp2 + 128 * j;
; #pragma unroll
;             for (int e2 = 0; e2 < 2; ++e2) { const int it = 2 * j + e2, kk = kk0 + e2;
;                 *(LAS v4u*)(L + ATT_KS + kk * ATT_KSTR + c8 * 16) = kwr[it];
;                 *(LAS v4u*)(L + ATT_VT + kk * ATT_VSTR + c8 * 16) = vwr[it]; }
;         }
;         const size_t orow = rowb + ((size_t)(m0 + 32 * wave + c) << dsh) + r;
;         bf16x8 qf[4];
; #pragma unroll
;         for (int s = 0; s < 4; ++s) qf[s] = __builtin_bit_cast(bf16x8, qwr[s]);
;         if (u + G < nunits) ATT_ISSUE(u + G);
;         __syncthreads();
;         f32x16 sc[5];
;         const LAS float* tb = (const LAS float*)(L + ATT_BIAS) + (32 + 4 * hh - c);
;         const int nskip = (m0 == 0 && wave < 4) ? 4 - wave : 0;
; #pragma unroll
;         for (int j = 0; j < 5; ++j) if (j >= nskip) {
; #pragma unroll
.LBB0_287:
	s_andn2_b64 vcc, exec, s[0:1]
	s_cbranch_vccnz .LBB0_328
	v_lshlrev_b32_e32 v4, 2, v2
	v_readlane_b32 s8, v236, 29
	v_sub_u32_e32 v7, v4, v0
	v_and_b32_e32 v8, 64, v190
	s_mul_i32 s0, s34, 0x1800
	v_lshl_add_u32 v197, v7, 2, s8
	v_xor_b32_e32 v7, 32, v190
	v_add_u32_e32 v8, 64, v8
	s_mul_hi_i32 s1, s34, 0x1800
	s_add_u32 s0, s24, s0
	v_cmp_lt_i32_e32 vcc, v7, v8
	s_addc_u32 s1, s25, s1
	s_lshl_b32 s10, s28, 5
	v_cndmask_b32_e32 v7, v190, v7, vcc
	s_movk_i32 s11, 0x120
	s_cmp_lt_i32 s28, 4
	v_lshlrev_b32_e32 v198, 2, v7
	v_mul_lo_u32 v7, v1, s11
	s_movk_i32 s11, 0x180
	s_cselect_b64 s[26:27], -1, 0
	v_mul_lo_u32 v1, v1, s11
	s_add_i32 s11, s10, 32
	v_lshrrev_b32_e32 v3, 2, v178
	v_and_b32_e32 v5, 16, v178
	v_lshlrev_b32_e32 v6, 2, v41
	v_or_b32_e32 v12, s11, v0
	s_add_i32 s11, s10, 64
	v_and_or_b32 v3, v3, 3, v4
	v_and_or_b32 v5, v6, 12, v5
	s_movk_i32 s12, 0xc0
	v_or_b32_e32 v195, s10, v0
	v_or_b32_e32 v8, 1, v179
	v_or_b32_e32 v13, s11, v0
	s_add_i32 s11, s10, 0x60
	s_addk_i32 s10, 0x80
	v_lshlrev_b32_e32 v5, 1, v5
	v_subrev_u32_e32 v6, 32, v178
	s_movk_i32 s6, 0x81
	s_sub_i32 s35, 4, s28
	v_mad_u32_u24 v3, v3, s12, 0
	s_movk_i32 s13, 0x90
	v_mul_lo_u32 v199, v8, s12
	v_or_b32_e32 v14, s11, v0
	v_or_b32_e32 v0, s10, v0
	s_mulk_i32 s28, 0x1800
	v_cmp_gt_u32_e64 s[6:7], s6, v6
	v_add_u32_e32 v194, 0, v112
	v_lshlrev_b32_e32 v6, 3, v2
	v_lshl_add_u32 v2, v2, 4, 0
	v_mul_lo_u32 v9, v8, s13
	v_add_u32_e32 v8, 0x5f40, v199
	v_add_u32_e32 v10, 0xbf40, v199
	v_mul_lo_u32 v11, v195, s13
	v_mul_lo_u32 v12, v12, s13
	v_mul_lo_u32 v13, v13, s13
	v_mul_lo_u32 v14, v14, s13
	v_mul_lo_u32 v0, v0, s13
	v_add3_u32 v200, v3, v5, s28
	v_cmp_gt_i32_e64 s[4:5], s12, v178
	v_lshl_add_u32 v193, v178, 2, s8
	v_add_u32_e32 v196, 0xffffff80, v179
	v_lshl_add_u64 v[180:181], s[22:23], 0, v[112:113]
	v_cmp_gt_u32_e64 s[8:9], 32, v41
	v_add_u32_e32 v201, 0xd800, v200
	v_add_u32_e32 v202, v194, v7
	v_add_u32_e32 v203, v194, v1
	v_add_u32_e32 v204, v194, v9
	v_add_u32_e32 v205, v194, v8
	v_add_u32_e32 v206, v194, v10
	v_lshlrev_b32_e32 v182, 1, v6
	v_add_u32_e32 v207, v2, v11
	v_add_u32_e32 v208, v2, v12
	v_add_u32_e32 v209, v2, v13
	v_add_u32_e32 v210, v2, v14
	v_add_u32_e32 v211, v2, v0
	v_lshlrev_b32_e32 v112, 1, v4
	s_mov_b32 s14, s2
	s_ashr_i32 s10, s14, 5
	s_mul_hi_i32 s12, s10, 0x55555556
	s_lshr_b32 s11, s12, 31
	s_add_i32 s12, s12, s11
	s_mul_i32 s11, s12, 3
	s_sub_i32 s11, s10, s11
	s_mul_i32 s11, s11, 0x204
	s_add_i32 s11, s11, 0x1fb00
	s_and_b32 s12, s12, 15
	s_and_b64 exec, s[4:5], s[6:7]
	s_cbranch_execz .Lmy_bias_f
	v_lshlrev_b32_e32 v221, 2, v178
	v_sub_u32_e32 v220, s11, v221
	ds_read_b32 v220, v220 offset:640
	s_waitcnt lgkmcnt(0)
	v_lshl_or_b32 v220, v220, 4, s12
	v_ashrrev_i32_e32 v221, 31, v220
	v_lshl_add_u64 v[220:221], v[220:221], 2, s[20:21]
	global_load_dword v220, v[220:221], off
.Lmy_bias_f:
	s_mov_b64 exec, -1
	s_branch .LBB0_290

; #define LAS __attribute__((address_space(3)))
; __device__ __forceinline__ void attn_mfma(const GAS bf16* proj, GAS bf16* part, GAS float* lse, int TOKG, const GAS float* qgain, const GAS float* kgain, const GAS float* rel_bias,
;                                           unsigned char* lds, int tid, int lane, int wave, int bid, int G) {
;     ...
;         ATT_DEC(u, )
;         __syncthreads();
;         if (tid < 192) { float tv = -INFINITY; const int dl = 160 - tid;
;             if (dl >= 0 && dl <= 128) tv = rel_bias[bkt[p * 129 + dl] * 16 + h] * 1.4426950408889634f;
;             ((LAS float*)(L + ATT_BIAS))[tid] = tv; }
.LBB0_290:
	s_ashr_i32 s10, s14, 5
	s_mul_hi_i32 s39, s10, 0x55555556
	s_lshr_b32 s11, s39, 31
	s_add_i32 s39, s39, s11
	s_mul_i32 s11, s39, 3
	s_sub_i32 s38, s10, s11
	s_and_b32 s36, s39, 15
	s_barrier
	s_and_saveexec_b64 s[10:11], s[4:5]
	s_cbranch_execz .LBB0_294
	v_mov_b32_e32 v96, 0xff800000
	s_and_saveexec_b64 s[12:13], s[6:7]
	s_cbranch_execz .LBB0_293
	s_waitcnt vmcnt(0)
	v_mul_f32_e32 v96, 0x3fb8aa3b, v220

; #define LAS __attribute__((address_space(3)))
; __device__ __forceinline__ void attn_mfma(const GAS bf16* proj, GAS bf16* part, GAS float* lse, int TOKG, const GAS float* qgain, const GAS float* kgain, const GAS float* rel_bias,
;                                           unsigned char* lds, int tid, int lane, int wave, int bid, int G) {
;     ...
;         for (int j = 0; j < 3; ++j) {
;             const int kk0 = 2 * rp2 + 128 * j;
; #pragma unroll
;             for (int e2 = 0; e2 < 2; ++e2) { const int it = 2 * j + e2, kk = kk0 + e2;
;                 *(LAS v4u*)(L + ATT_KS + kk * ATT_KSTR + c8 * 16) = kwr[it];
;                 *(LAS v4u*)(L + ATT_VT + kk * ATT_VSTR + c8 * 16) = vwr[it]; }
;         }
;         const size_t orow = rowb + ((size_t)(m0 + 32 * wave + c) << dsh) + r;
;         bf16x8 qf[4];
; #pragma unroll
;         for (int s = 0; s < 4; ++s) qf[s] = __builtin_bit_cast(bf16x8, qwr[s]);
;         if (u + G < nunits) ATT_ISSUE(u + G);
.LBB0_294:
	s_or_b64 exec, exec, s[10:11]
	s_add_i32 s37, s14, s50
	s_cmp_ge_i32 s37, s3
	s_cselect_b64 s[28:29], -1, 0
	s_waitcnt vmcnt(0)
	v_mov_b64_e32 v[176:177], v[82:83]
	v_mov_b64_e32 v[168:169], v[86:87]
	v_mov_b64_e32 v[164:165], v[90:91]
	v_mov_b64_e32 v[172:173], v[94:95]
	v_add_u32_e32 v96, v194, v199
	s_and_b64 vcc, exec, s[28:29]
	v_mov_b64_e32 v[174:175], v[80:81]
	v_mov_b64_e32 v[166:167], v[84:85]
	v_mov_b64_e32 v[162:163], v[88:89]
	v_mov_b64_e32 v[170:171], v[92:93]
	ds_write_b128 v202, v[114:117]
	ds_write_b128 v203, v[118:121] offset:55296
	ds_write_b128 v204, v[122:125]
	ds_write_b128 v96, v[126:129] offset:55296
	ds_write_b128 v204, v[134:137] offset:18288
	ds_write_b128 v205, v[130:133] offset:55296
	ds_write_b128 v204, v[142:145] offset:18432
	ds_write_b128 v205, v[138:141] offset:55488
	ds_write_b128 v204, v[150:153] offset:36720
	ds_write_b128 v206, v[146:149] offset:55296
	ds_write_b128 v204, v[158:161] offset:36864
	ds_write_b128 v206, v[154:157] offset:55488
	s_cbranch_vccnz .LBB0_296
	s_ashr_i32 s10, s37, 5
	s_mul_hi_i32 s12, s10, 0x55555556
	s_lshr_b32 s13, s12, 31
	s_add_i32 s12, s12, s13
	s_mul_i32 s13, s12, 3
	s_sub_i32 s13, s10, s13
	s_lshl_b32 s13, s13, 1
	s_lshr_b32 s17, s13, 1
	s_mul_i32 s17, s17, 0x204
	s_add_i32 s17, s17, 0x1fb00
	s_and_b32 s18, s12, 15
	s_and_b64 exec, s[4:5], s[6:7]
	s_cbranch_execz .Lmy_bias_n1
	v_lshlrev_b32_e32 v221, 2, v178
	v_sub_u32_e32 v220, s17, v221
	ds_read_b32 v220, v220 offset:640
.Lmy_bias_n1:
	s_mov_b64 exec, -1
	s_and_b32 s11, s37, 31
	s_lshl_b32 s15, -1, s13
	s_andn2_b32 s15, s11, s15
	s_lshr_b32 s11, s11, s13
	s_ashr_i32 s10, s12, 4
	s_lshl_b32 s16, s11, 8
	s_ashr_i32 s11, s10, 31
	v_add_u32_e32 v100, s16, v196
	s_lshl_b64 s[10:11], s[10:11], 13
	v_max_i32_e32 v98, 0, v100
	v_mov_b32_e32 v99, v113
	s_or_b32 s10, s10, s15
	s_lshl_b32 s12, s12, 7
	v_lshlrev_b64 v[98:99], s13, v[98:99]
	s_and_b32 s60, s12, 0x780
	v_lshl_add_u64 v[98:99], v[98:99], 0, s[10:11]
	v_lshl_add_u64 v[96:97], v[180:181], 0, s[60:61]
	v_lshlrev_b64 v[98:99], 14, v[98:99]
	v_lshl_add_u64 v[98:99], v[96:97], 0, v[98:99]
	v_add_co_u32_e32 v98, vcc, s93, v98
	v_mov_b32_e32 v183, v113
	s_nop 0
	v_addc_co_u32_e32 v99, vcc, 0, v99, vcc
	global_load_dwordx4 v[114:117], v[98:99], off
	global_load_dwordx4 v[118:121], v[98:99], off offset:2048
	v_or_b32_e32 v98, 1, v100
	v_max_i32_e32 v98, 0, v98
	v_mov_b32_e32 v99, v113
	v_lshlrev_b64 v[98:99], s13, v[98:99]
	v_lshl_add_u64 v[98:99], v[98:99], 0, s[10:11]
	v_lshlrev_b64 v[98:99], 14, v[98:99]
	v_lshl_add_u64 v[98:99], v[96:97], 0, v[98:99]
	v_add_co_u32_e32 v98, vcc, s93, v98
	s_nop 1
	v_addc_co_u32_e32 v99, vcc, 0, v99, vcc
	global_load_dwordx4 v[122:125], v[98:99], off
	global_load_dwordx4 v[126:129], v[98:99], off offset:2048
	v_add_u32_e32 v98, s16, v179
	v_max_i32_e32 v98, 0, v98
	v_mov_b32_e32 v99, v113
	v_lshlrev_b64 v[98:99], s13, v[98:99]
	v_lshl_add_u64 v[98:99], v[98:99], 0, s[10:11]
	v_lshlrev_b64 v[98:99], 14, v[98:99]
	v_lshl_add_u64 v[98:99], v[96:97], 0, v[98:99]
	v_add_co_u32_e32 v98, vcc, s93, v98
	s_nop 1
	v_addc_co_u32_e32 v99, vcc, 0, v99, vcc
	global_load_dwordx4 v[134:137], v[98:99], off
	global_load_dwordx4 v[130:133], v[98:99], off offset:2048
	v_max_i32_e32 v98, 0xffffff7f, v100
	v_add_u32_e32 v98, 0x81, v98
	v_mov_b32_e32 v99, v113
	v_lshlrev_b64 v[98:99], s13, v[98:99]
	v_lshl_add_u64 v[98:99], v[98:99], 0, s[10:11]
	v_lshlrev_b64 v[98:99], 14, v[98:99]
	v_lshl_add_u64 v[98:99], v[96:97], 0, v[98:99]
	v_add_co_u32_e32 v98, vcc, s93, v98
	s_nop 1
	v_addc_co_u32_e32 v99, vcc, 0, v99, vcc
	global_load_dwordx4 v[142:145], v[98:99], off
	global_load_dwordx4 v[138:141], v[98:99], off offset:2048
	v_max_i32_e32 v98, 0xffffff00, v100
	v_add_u32_e32 v98, 0x100, v98
	v_mov_b32_e32 v99, v113
	v_lshlrev_b64 v[98:99], s13, v[98:99]
	v_lshl_add_u64 v[98:99], v[98:99], 0, s[10:11]
	v_lshlrev_b64 v[98:99], 14, v[98:99]
	v_lshl_add_u64 v[98:99], v[96:97], 0, v[98:99]
	v_add_co_u32_e32 v98, vcc, s93, v98
	s_nop 1
	v_addc_co_u32_e32 v99, vcc, 0, v99, vcc
	global_load_dwordx4 v[150:153], v[98:99], off
	global_load_dwordx4 v[146:149], v[98:99], off offset:2048
	v_max_i32_e32 v98, 0xfffffeff, v100
	v_add_u32_e32 v98, 0x101, v98
	v_mov_b32_e32 v99, v113
	v_lshlrev_b64 v[98:99], s13, v[98:99]
	v_lshl_add_u64 v[98:99], v[98:99], 0, s[10:11]
	v_lshlrev_b64 v[98:99], 14, v[98:99]
	v_lshl_add_u64 v[96:97], v[96:97], 0, v[98:99]
	v_add_co_u32_e32 v96, vcc, s93, v96
	s_nop 1
	v_addc_co_u32_e32 v97, vcc, 0, v97, vcc
	global_load_dwordx4 v[158:161], v[96:97], off
	global_load_dwordx4 v[154:157], v[96:97], off offset:2048
	v_add_u32_e32 v96, s16, v195
	v_ashrrev_i32_e32 v97, 31, v96
	v_lshlrev_b64 v[96:97], s13, v[96:97]
	v_lshl_add_u64 v[96:97], v[96:97], 0, s[10:11]
	v_lshlrev_b64 v[96:97], 14, v[96:97]
	v_lshl_add_u64 v[96:97], s[22:23], 0, v[96:97]
	v_lshl_add_u64 v[96:97], v[96:97], 0, s[60:61]
	v_lshl_add_u64 v[96:97], v[96:97], 0, v[182:183]
	v_lshl_add_u64 v[98:99], v[96:97], 0, s[98:99]
	v_add_co_u32_e32 v96, vcc, 0x1000, v96
	s_nop 1
	v_addc_co_u32_e32 v97, vcc, 0, v97, vcc
	global_load_dwordx4 v[162:165], v[98:99], off offset:32
	global_load_dwordx4 v[166:169], v[98:99], off offset:64
	global_load_dwordx4 v[170:173], v[96:97], off offset:2048
	global_load_dwordx4 v[174:177], v[98:99], off offset:96
	s_and_b64 exec, s[4:5], s[6:7]
	s_cbranch_execz .Lmy_bias_n2
	s_waitcnt lgkmcnt(0)
	v_lshl_or_b32 v220, v220, 4, s18
	v_ashrrev_i32_e32 v221, 31, v220
	v_lshl_add_u64 v[220:221], v[220:221], 2, s[20:21]
	global_load_dword v220, v[220:221], off
.Lmy_bias_n2:
	s_mov_b64 exec, -1
